# code placement: the eight GEMM K-loop heads aligned to 64 bytes (p2align 6), no instruction changes
# baseline (speedup 1.0000x reference)
; #define LAS __attribute__((address_space(3)))
;     ...
;         const bool has_next = S.next(ui + 1, nxt);
;         const unsigned rsoff = (unsigned)STAGE_BYTES + (unsigned)(ui & 1) * 1024u;
;         if constexpr (Epi::NEEDS_RS) { if (wid < 4) __builtin_amdgcn_global_load_lds((const unsigned*)(E.rsv + cur.pm * 256 + wid * 64 + lane), (LAS unsigned*)(lds + rsoff + wid * 256), 4, 0, 0); }
;         const char* nA = has_next ? (const char*)g.A + (size_t)nxt.pm * tstepA + (size_t)nxt.pn * APN : cA; const char* nB = has_next ? (const char*)g.Bt + (size_t)nxt.pn * tstepB : cB;
;         for (int t = 0; t < nt; t += 2) {
;             const bool last = (t == nt - 2);
;             const char* a1 = cA + (size_t)(t + 1) * kstep;
;             const char* a2 = last ? nA : cA + (size_t)(t + 2) * kstep; const char* b2 = last ? nB : cB + (size_t)(t + 2) * kstep;
;             const char* a3 = a2 + kstep; const char* b3 = b2 + kstep;
;     ...
; #pragma unroll
;         for (int a = 0; a < 2; ++a)
; #pragma unroll
;             for (int b = 0; b < 2; ++b)
; #pragma unroll
;                 for (int m = 0; m < 4; ++m)
; #pragma unroll
;                     for (int n = 0; n < 2; ++n) acc[a][b][m][n] = (f32x4){0.f, 0.f, 0.f, 0.f};
;         cur = nxt; cA = nA; cB = nB; ++ui;
.LBB0_82:
	v_mov_b32_e32 v127, 0
	s_andn2_b64 vcc, exec, s[24:25]
	v_mov_b32_e32 v126, v127
	v_mov_b32_e32 v125, v127
	v_mov_b32_e32 v124, v127
	v_mov_b32_e32 v123, v127
	v_mov_b32_e32 v122, v127
	v_mov_b32_e32 v121, v127
	v_mov_b32_e32 v120, v127
	v_mov_b32_e32 v111, v127
	v_mov_b32_e32 v110, v127
	v_mov_b32_e32 v109, v127
	v_mov_b32_e32 v108, v127
	v_mov_b32_e32 v107, v127
	v_mov_b32_e32 v106, v127
	v_mov_b32_e32 v105, v127
	v_mov_b32_e32 v104, v127
	v_mov_b32_e32 v95, v127
	v_mov_b32_e32 v94, v127
	v_mov_b32_e32 v93, v127
	v_mov_b32_e32 v92, v127
	v_mov_b32_e32 v91, v127
	v_mov_b32_e32 v90, v127
	v_mov_b32_e32 v89, v127
	v_mov_b32_e32 v88, v127
	v_mov_b32_e32 v79, v127
	v_mov_b32_e32 v78, v127
	v_mov_b32_e32 v77, v127
	v_mov_b32_e32 v76, v127
	v_mov_b32_e32 v75, v127
	v_mov_b32_e32 v74, v127
	v_mov_b32_e32 v73, v127
	v_mov_b32_e32 v72, v127
	v_mov_b32_e32 v119, v127
	v_mov_b32_e32 v118, v127
	v_mov_b32_e32 v117, v127
	v_mov_b32_e32 v116, v127
	v_mov_b32_e32 v115, v127
	v_mov_b32_e32 v114, v127
	v_mov_b32_e32 v113, v127
	v_mov_b32_e32 v112, v127
	v_mov_b32_e32 v103, v127
	v_mov_b32_e32 v102, v127
	v_mov_b32_e32 v101, v127
	v_mov_b32_e32 v100, v127
	v_mov_b32_e32 v99, v127
	v_mov_b32_e32 v98, v127
	v_mov_b32_e32 v97, v127
	v_mov_b32_e32 v96, v127
	v_mov_b32_e32 v87, v127
	v_mov_b32_e32 v86, v127
	v_mov_b32_e32 v85, v127
	v_mov_b32_e32 v84, v127
	v_mov_b32_e32 v83, v127
	v_mov_b32_e32 v82, v127
	v_mov_b32_e32 v81, v127
	v_mov_b32_e32 v80, v127
	v_mov_b32_e32 v71, v127
	v_mov_b32_e32 v70, v127
	v_mov_b32_e32 v69, v127
	v_mov_b32_e32 v68, v127
	v_mov_b32_e32 v67, v127
	v_mov_b32_e32 v66, v127
	v_mov_b32_e32 v65, v127
	v_mov_b32_e32 v64, v127
	v_mov_b32_e32 v63, v127
	v_mov_b32_e32 v62, v127
	v_mov_b32_e32 v61, v127
	v_mov_b32_e32 v60, v127
	v_mov_b32_e32 v59, v127
	v_mov_b32_e32 v58, v127
	v_mov_b32_e32 v57, v127
	v_mov_b32_e32 v56, v127
	v_mov_b32_e32 v47, v127
	v_mov_b32_e32 v46, v127
	v_mov_b32_e32 v45, v127
	v_mov_b32_e32 v44, v127
	v_mov_b32_e32 v43, v127
	v_mov_b32_e32 v42, v127
	v_mov_b32_e32 v41, v127
	v_mov_b32_e32 v40, v127
	v_mov_b32_e32 v31, v127
	v_mov_b32_e32 v30, v127
	v_mov_b32_e32 v29, v127
	v_mov_b32_e32 v28, v127
	v_mov_b32_e32 v27, v127
	v_mov_b32_e32 v26, v127
	v_mov_b32_e32 v25, v127
	v_mov_b32_e32 v24, v127
	v_mov_b32_e32 v15, v127
	v_mov_b32_e32 v14, v127
	v_mov_b32_e32 v13, v127
	v_mov_b32_e32 v12, v127
	v_mov_b32_e32 v11, v127
	v_mov_b32_e32 v10, v127
	v_mov_b32_e32 v9, v127
	v_mov_b32_e32 v8, v127
	v_mov_b32_e32 v55, v127
	v_mov_b32_e32 v54, v127
	v_mov_b32_e32 v53, v127
	v_mov_b32_e32 v52, v127
	v_mov_b32_e32 v51, v127
	v_mov_b32_e32 v50, v127
	v_mov_b32_e32 v49, v127
	v_mov_b32_e32 v48, v127
	v_mov_b32_e32 v39, v127
	v_mov_b32_e32 v38, v127
	v_mov_b32_e32 v37, v127
	v_mov_b32_e32 v36, v127
	v_mov_b32_e32 v35, v127
	v_mov_b32_e32 v34, v127
	v_mov_b32_e32 v33, v127
	v_mov_b32_e32 v32, v127
	v_mov_b32_e32 v23, v127
	v_mov_b32_e32 v22, v127
	v_mov_b32_e32 v21, v127
	v_mov_b32_e32 v20, v127
	v_mov_b32_e32 v19, v127
	v_mov_b32_e32 v18, v127
	v_mov_b32_e32 v17, v127
	v_mov_b32_e32 v16, v127
	v_mov_b32_e32 v7, v127
	v_mov_b32_e32 v6, v127
	v_mov_b32_e32 v5, v127
	v_mov_b32_e32 v4, v127
	v_mov_b32_e32 v3, v127
	v_mov_b32_e32 v2, v127
	s_waitcnt lgkmcnt(0)
	v_mov_b32_e32 v1, v127
	v_mov_b32_e32 v0, v127
	s_cbranch_vccnz .LBB0_85
	s_add_u32 s14, s4, 0x100
	v_mov_b32_e32 v0, 0
	s_addc_u32 s15, s5, 0
	s_mov_b32 s8, 0
	v_mov_b32_e32 v1, v0
	v_mov_b32_e32 v2, v0
	v_mov_b32_e32 v3, v0
	v_mov_b32_e32 v4, v0
	v_mov_b32_e32 v5, v0
	v_mov_b32_e32 v6, v0
	v_mov_b32_e32 v7, v0
	v_mov_b32_e32 v16, v0
	v_mov_b32_e32 v17, v0
	v_mov_b32_e32 v18, v0
	v_mov_b32_e32 v19, v0
	v_mov_b32_e32 v20, v0
	v_mov_b32_e32 v21, v0
	v_mov_b32_e32 v22, v0
	v_mov_b32_e32 v23, v0
	v_mov_b32_e32 v32, v0
	v_mov_b32_e32 v33, v0
	v_mov_b32_e32 v34, v0
	v_mov_b32_e32 v35, v0
	v_mov_b32_e32 v36, v0
	v_mov_b32_e32 v37, v0
	v_mov_b32_e32 v38, v0
	v_mov_b32_e32 v39, v0
	v_mov_b32_e32 v48, v0
	v_mov_b32_e32 v49, v0
	v_mov_b32_e32 v50, v0
	v_mov_b32_e32 v51, v0
	v_mov_b32_e32 v52, v0
	v_mov_b32_e32 v53, v0
	v_mov_b32_e32 v54, v0
	v_mov_b32_e32 v55, v0
	v_mov_b32_e32 v8, v0
	v_mov_b32_e32 v9, v0
	v_mov_b32_e32 v10, v0
	v_mov_b32_e32 v11, v0
	v_mov_b32_e32 v12, v0
	v_mov_b32_e32 v13, v0
	v_mov_b32_e32 v14, v0
	v_mov_b32_e32 v15, v0
	v_mov_b32_e32 v24, v0
	v_mov_b32_e32 v25, v0
	v_mov_b32_e32 v26, v0
	v_mov_b32_e32 v27, v0
	v_mov_b32_e32 v28, v0
	v_mov_b32_e32 v29, v0
	v_mov_b32_e32 v30, v0
	v_mov_b32_e32 v31, v0
	v_mov_b32_e32 v40, v0
	v_mov_b32_e32 v41, v0
	v_mov_b32_e32 v42, v0
	v_mov_b32_e32 v43, v0
	v_mov_b32_e32 v44, v0
	v_mov_b32_e32 v45, v0
	v_mov_b32_e32 v46, v0
	v_mov_b32_e32 v47, v0
	v_mov_b32_e32 v56, v0
	v_mov_b32_e32 v57, v0
	v_mov_b32_e32 v58, v0
	v_mov_b32_e32 v59, v0
	v_mov_b32_e32 v60, v0
	v_mov_b32_e32 v61, v0
	v_mov_b32_e32 v62, v0
	v_mov_b32_e32 v63, v0
	v_mov_b32_e32 v64, v0
	v_mov_b32_e32 v65, v0
	v_mov_b32_e32 v66, v0
	v_mov_b32_e32 v67, v0
	v_mov_b32_e32 v68, v0
	v_mov_b32_e32 v69, v0
	v_mov_b32_e32 v70, v0
	v_mov_b32_e32 v71, v0
	v_mov_b32_e32 v80, v0
	v_mov_b32_e32 v81, v0
	v_mov_b32_e32 v82, v0
	v_mov_b32_e32 v83, v0
	v_mov_b32_e32 v84, v0
	v_mov_b32_e32 v85, v0
	v_mov_b32_e32 v86, v0
	v_mov_b32_e32 v87, v0
	v_mov_b32_e32 v96, v0
	v_mov_b32_e32 v97, v0
	v_mov_b32_e32 v98, v0
	v_mov_b32_e32 v99, v0
	v_mov_b32_e32 v100, v0
	v_mov_b32_e32 v101, v0
	v_mov_b32_e32 v102, v0
	v_mov_b32_e32 v103, v0
	v_mov_b32_e32 v112, v0
	v_mov_b32_e32 v113, v0
	v_mov_b32_e32 v114, v0
	v_mov_b32_e32 v115, v0
	v_mov_b32_e32 v116, v0
	v_mov_b32_e32 v117, v0
	v_mov_b32_e32 v118, v0
	v_mov_b32_e32 v119, v0
	v_mov_b32_e32 v72, v0
	v_mov_b32_e32 v73, v0
	v_mov_b32_e32 v74, v0
	v_mov_b32_e32 v75, v0
	v_mov_b32_e32 v76, v0
	v_mov_b32_e32 v77, v0
	v_mov_b32_e32 v78, v0
	v_mov_b32_e32 v79, v0
	v_mov_b32_e32 v88, v0
	v_mov_b32_e32 v89, v0
	v_mov_b32_e32 v90, v0
	v_mov_b32_e32 v91, v0
	v_mov_b32_e32 v92, v0
	v_mov_b32_e32 v93, v0
	v_mov_b32_e32 v94, v0
	v_mov_b32_e32 v95, v0
	v_mov_b32_e32 v104, v0
	v_mov_b32_e32 v105, v0
	v_mov_b32_e32 v106, v0
	v_mov_b32_e32 v107, v0
	v_mov_b32_e32 v108, v0
	v_mov_b32_e32 v109, v0
	v_mov_b32_e32 v110, v0
	v_mov_b32_e32 v111, v0
	v_mov_b32_e32 v120, v0
	v_mov_b32_e32 v121, v0
	v_mov_b32_e32 v122, v0
	v_mov_b32_e32 v123, v0
	v_mov_b32_e32 v124, v0
	v_mov_b32_e32 v125, v0
	v_mov_b32_e32 v126, v0
	v_mov_b32_e32 v127, v0
	s_mov_b64 s[58:59], 0x80
	.p2align	6

; #define LAS __attribute__((address_space(3)))
;     ...
;         const bool has_next = S.next(ui + 1, nxt);
;         const unsigned rsoff = (unsigned)STAGE_BYTES + (unsigned)(ui & 1) * 1024u;
;         if constexpr (Epi::NEEDS_RS) { if (wid < 4) __builtin_amdgcn_global_load_lds((const unsigned*)(E.rsv + cur.pm * 256 + wid * 64 + lane), (LAS unsigned*)(lds + rsoff + wid * 256), 4, 0, 0); }
;         const char* nA = has_next ? (const char*)g.A + (size_t)nxt.pm * tstepA + (size_t)nxt.pn * APN : cA; const char* nB = has_next ? (const char*)g.Bt + (size_t)nxt.pn * tstepB : cB;
;         for (int t = 0; t < nt; t += 2) {
;             const bool last = (t == nt - 2);
;             const char* a1 = cA + (size_t)(t + 1) * kstep;
;             const char* a2 = last ? nA : cA + (size_t)(t + 2) * kstep; const char* b2 = last ? nB : cB + (size_t)(t + 2) * kstep;
;             const char* a3 = a2 + kstep; const char* b3 = b2 + kstep;
;     ...
; #pragma unroll
;         for (int a = 0; a < 2; ++a)
; #pragma unroll
;             for (int b = 0; b < 2; ++b)
; #pragma unroll
;                 for (int m = 0; m < 4; ++m)
; #pragma unroll
;                     for (int n = 0; n < 2; ++n) acc[a][b][m][n] = (f32x4){0.f, 0.f, 0.f, 0.f};
;         cur = nxt; cA = nA; cB = nB; ++ui;
.LBB0_131:
	v_mov_b32_e32 v127, 0
	s_andn2_b64 vcc, exec, s[28:29]
	v_mov_b32_e32 v126, v127
	v_mov_b32_e32 v125, v127
	v_mov_b32_e32 v124, v127
	v_mov_b32_e32 v123, v127
	v_mov_b32_e32 v122, v127
	v_mov_b32_e32 v121, v127
	v_mov_b32_e32 v120, v127
	v_mov_b32_e32 v111, v127
	v_mov_b32_e32 v110, v127
	v_mov_b32_e32 v109, v127
	v_mov_b32_e32 v108, v127
	v_mov_b32_e32 v107, v127
	v_mov_b32_e32 v106, v127
	v_mov_b32_e32 v105, v127
	v_mov_b32_e32 v104, v127
	v_mov_b32_e32 v95, v127
	v_mov_b32_e32 v94, v127
	v_mov_b32_e32 v93, v127
	v_mov_b32_e32 v92, v127
	v_mov_b32_e32 v91, v127
	v_mov_b32_e32 v90, v127
	v_mov_b32_e32 v89, v127
	v_mov_b32_e32 v88, v127
	v_mov_b32_e32 v79, v127
	v_mov_b32_e32 v78, v127
	v_mov_b32_e32 v77, v127
	v_mov_b32_e32 v76, v127
	v_mov_b32_e32 v75, v127
	v_mov_b32_e32 v74, v127
	v_mov_b32_e32 v73, v127
	v_mov_b32_e32 v72, v127
	v_mov_b32_e32 v119, v127
	v_mov_b32_e32 v118, v127
	v_mov_b32_e32 v117, v127
	v_mov_b32_e32 v116, v127
	v_mov_b32_e32 v115, v127
	v_mov_b32_e32 v114, v127
	v_mov_b32_e32 v113, v127
	v_mov_b32_e32 v112, v127
	v_mov_b32_e32 v103, v127
	v_mov_b32_e32 v102, v127
	v_mov_b32_e32 v101, v127
	v_mov_b32_e32 v100, v127
	v_mov_b32_e32 v99, v127
	v_mov_b32_e32 v98, v127
	v_mov_b32_e32 v97, v127
	v_mov_b32_e32 v96, v127
	v_mov_b32_e32 v87, v127
	v_mov_b32_e32 v86, v127
	v_mov_b32_e32 v85, v127
	v_mov_b32_e32 v84, v127
	v_mov_b32_e32 v83, v127
	v_mov_b32_e32 v82, v127
	v_mov_b32_e32 v81, v127
	v_mov_b32_e32 v80, v127
	v_mov_b32_e32 v71, v127
	v_mov_b32_e32 v70, v127
	v_mov_b32_e32 v69, v127
	v_mov_b32_e32 v68, v127
	v_mov_b32_e32 v67, v127
	v_mov_b32_e32 v66, v127
	v_mov_b32_e32 v65, v127
	v_mov_b32_e32 v64, v127
	v_mov_b32_e32 v63, v127
	v_mov_b32_e32 v62, v127
	v_mov_b32_e32 v61, v127
	v_mov_b32_e32 v60, v127
	v_mov_b32_e32 v59, v127
	v_mov_b32_e32 v58, v127
	v_mov_b32_e32 v57, v127
	v_mov_b32_e32 v56, v127
	v_mov_b32_e32 v47, v127
	v_mov_b32_e32 v46, v127
	v_mov_b32_e32 v45, v127
	v_mov_b32_e32 v44, v127
	v_mov_b32_e32 v43, v127
	v_mov_b32_e32 v42, v127
	v_mov_b32_e32 v41, v127
	v_mov_b32_e32 v40, v127
	v_mov_b32_e32 v31, v127
	v_mov_b32_e32 v30, v127
	v_mov_b32_e32 v29, v127
	v_mov_b32_e32 v28, v127
	v_mov_b32_e32 v27, v127
	v_mov_b32_e32 v26, v127
	v_mov_b32_e32 v25, v127
	v_mov_b32_e32 v24, v127
	v_mov_b32_e32 v15, v127
	v_mov_b32_e32 v14, v127
	v_mov_b32_e32 v13, v127
	v_mov_b32_e32 v12, v127
	v_mov_b32_e32 v11, v127
	v_mov_b32_e32 v10, v127
	v_mov_b32_e32 v9, v127
	v_mov_b32_e32 v8, v127
	v_mov_b32_e32 v55, v127
	v_mov_b32_e32 v54, v127
	v_mov_b32_e32 v53, v127
	v_mov_b32_e32 v52, v127
	v_mov_b32_e32 v51, v127
	v_mov_b32_e32 v50, v127
	v_mov_b32_e32 v49, v127
	v_mov_b32_e32 v48, v127
	v_mov_b32_e32 v39, v127
	v_mov_b32_e32 v38, v127
	v_mov_b32_e32 v37, v127
	v_mov_b32_e32 v36, v127
	v_mov_b32_e32 v35, v127
	v_mov_b32_e32 v34, v127
	v_mov_b32_e32 v33, v127
	v_mov_b32_e32 v32, v127
	v_mov_b32_e32 v23, v127
	v_mov_b32_e32 v22, v127
	v_mov_b32_e32 v21, v127
	v_mov_b32_e32 v20, v127
	v_mov_b32_e32 v19, v127
	v_mov_b32_e32 v18, v127
	v_mov_b32_e32 v17, v127
	v_mov_b32_e32 v16, v127
	v_mov_b32_e32 v7, v127
	v_mov_b32_e32 v6, v127
	v_mov_b32_e32 v5, v127
	v_mov_b32_e32 v4, v127
	v_mov_b32_e32 v3, v127
	v_mov_b32_e32 v2, v127
	v_mov_b32_e32 v1, v127
	v_mov_b32_e32 v0, v127
	s_cbranch_vccnz .LBB0_135
	s_add_u32 s7, s2, 0x100
	v_mov_b32_e32 v0, 0
	v_mov_b64_e32 v[212:213], 0x77f
	v_mov_b64_e32 v[154:155], 0x780
	s_addc_u32 s8, s3, 0
	s_mov_b32 s4, 0
	v_mov_b32_e32 v1, v0
	v_mov_b32_e32 v2, v0
	v_mov_b32_e32 v3, v0
	v_mov_b32_e32 v4, v0
	v_mov_b32_e32 v5, v0
	v_mov_b32_e32 v6, v0
	v_mov_b32_e32 v7, v0
	v_mov_b32_e32 v16, v0
	v_mov_b32_e32 v17, v0
	v_mov_b32_e32 v18, v0
	v_mov_b32_e32 v19, v0
	v_mov_b32_e32 v20, v0
	v_mov_b32_e32 v21, v0
	v_mov_b32_e32 v22, v0
	v_mov_b32_e32 v23, v0
	v_mov_b32_e32 v32, v0
	v_mov_b32_e32 v33, v0
	v_mov_b32_e32 v34, v0
	v_mov_b32_e32 v35, v0
	v_mov_b32_e32 v36, v0
	v_mov_b32_e32 v37, v0
	v_mov_b32_e32 v38, v0
	v_mov_b32_e32 v39, v0
	v_mov_b32_e32 v48, v0
	v_mov_b32_e32 v49, v0
	v_mov_b32_e32 v50, v0
	v_mov_b32_e32 v51, v0
	v_mov_b32_e32 v52, v0
	v_mov_b32_e32 v53, v0
	v_mov_b32_e32 v54, v0
	v_mov_b32_e32 v55, v0
	v_mov_b32_e32 v8, v0
	v_mov_b32_e32 v9, v0
	v_mov_b32_e32 v10, v0
	v_mov_b32_e32 v11, v0
	v_mov_b32_e32 v12, v0
	v_mov_b32_e32 v13, v0
	v_mov_b32_e32 v14, v0
	v_mov_b32_e32 v15, v0
	v_mov_b32_e32 v24, v0
	v_mov_b32_e32 v25, v0
	v_mov_b32_e32 v26, v0
	v_mov_b32_e32 v27, v0
	v_mov_b32_e32 v28, v0
	v_mov_b32_e32 v29, v0
	v_mov_b32_e32 v30, v0
	v_mov_b32_e32 v31, v0
	v_mov_b32_e32 v40, v0
	v_mov_b32_e32 v41, v0
	v_mov_b32_e32 v42, v0
	v_mov_b32_e32 v43, v0
	v_mov_b32_e32 v44, v0
	v_mov_b32_e32 v45, v0
	v_mov_b32_e32 v46, v0
	v_mov_b32_e32 v47, v0
	v_mov_b32_e32 v56, v0
	v_mov_b32_e32 v57, v0
	v_mov_b32_e32 v58, v0
	v_mov_b32_e32 v59, v0
	v_mov_b32_e32 v60, v0
	v_mov_b32_e32 v61, v0
	v_mov_b32_e32 v62, v0
	v_mov_b32_e32 v63, v0
	v_mov_b32_e32 v64, v0
	v_mov_b32_e32 v65, v0
	v_mov_b32_e32 v66, v0
	v_mov_b32_e32 v67, v0
	v_mov_b32_e32 v68, v0
	v_mov_b32_e32 v69, v0
	v_mov_b32_e32 v70, v0
	v_mov_b32_e32 v71, v0
	v_mov_b32_e32 v80, v0
	v_mov_b32_e32 v81, v0
	v_mov_b32_e32 v82, v0
	v_mov_b32_e32 v83, v0
	v_mov_b32_e32 v84, v0
	v_mov_b32_e32 v85, v0
	v_mov_b32_e32 v86, v0
	v_mov_b32_e32 v87, v0
	v_mov_b32_e32 v96, v0
	v_mov_b32_e32 v97, v0
	v_mov_b32_e32 v98, v0
	v_mov_b32_e32 v99, v0
	v_mov_b32_e32 v100, v0
	v_mov_b32_e32 v101, v0
	v_mov_b32_e32 v102, v0
	v_mov_b32_e32 v103, v0
	v_mov_b32_e32 v112, v0
	v_mov_b32_e32 v113, v0
	v_mov_b32_e32 v114, v0
	v_mov_b32_e32 v115, v0
	v_mov_b32_e32 v116, v0
	v_mov_b32_e32 v117, v0
	v_mov_b32_e32 v118, v0
	v_mov_b32_e32 v119, v0
	v_mov_b32_e32 v72, v0
	v_mov_b32_e32 v73, v0
	v_mov_b32_e32 v74, v0
	v_mov_b32_e32 v75, v0
	v_mov_b32_e32 v76, v0
	v_mov_b32_e32 v77, v0
	v_mov_b32_e32 v78, v0
	v_mov_b32_e32 v79, v0
	v_mov_b32_e32 v88, v0
	v_mov_b32_e32 v89, v0
	v_mov_b32_e32 v90, v0
	v_mov_b32_e32 v91, v0
	v_mov_b32_e32 v92, v0
	v_mov_b32_e32 v93, v0
	v_mov_b32_e32 v94, v0
	v_mov_b32_e32 v95, v0
	v_mov_b32_e32 v104, v0
	v_mov_b32_e32 v105, v0
	v_mov_b32_e32 v106, v0
	v_mov_b32_e32 v107, v0
	v_mov_b32_e32 v108, v0
	v_mov_b32_e32 v109, v0
	v_mov_b32_e32 v110, v0
	v_mov_b32_e32 v111, v0
	v_mov_b32_e32 v120, v0
	v_mov_b32_e32 v121, v0
	v_mov_b32_e32 v122, v0
	v_mov_b32_e32 v123, v0
	v_mov_b32_e32 v124, v0
	v_mov_b32_e32 v125, v0
	v_mov_b32_e32 v126, v0
	v_mov_b32_e32 v127, v0
	s_mov_b64 s[58:59], 0x80
	.p2align	6

; #define LAS __attribute__((address_space(3)))
;     ...
;         const bool has_next = S.next(ui + 1, nxt);
;         const unsigned rsoff = (unsigned)STAGE_BYTES + (unsigned)(ui & 1) * 1024u;
;         if constexpr (Epi::NEEDS_RS) { if (wid < 4) __builtin_amdgcn_global_load_lds((const unsigned*)(E.rsv + cur.pm * 256 + wid * 64 + lane), (LAS unsigned*)(lds + rsoff + wid * 256), 4, 0, 0); }
;         const char* nA = has_next ? (const char*)g.A + (size_t)nxt.pm * tstepA + (size_t)nxt.pn * APN : cA; const char* nB = has_next ? (const char*)g.Bt + (size_t)nxt.pn * tstepB : cB;
;         for (int t = 0; t < nt; t += 2) {
;             const bool last = (t == nt - 2);
;             const char* a1 = cA + (size_t)(t + 1) * kstep;
;             const char* a2 = last ? nA : cA + (size_t)(t + 2) * kstep; const char* b2 = last ? nB : cB + (size_t)(t + 2) * kstep;
;             const char* a3 = a2 + kstep; const char* b3 = b2 + kstep;
;     ...
; #pragma unroll
;         for (int a = 0; a < 2; ++a)
; #pragma unroll
;             for (int b = 0; b < 2; ++b)
; #pragma unroll
;                 for (int m = 0; m < 4; ++m)
; #pragma unroll
;                     for (int n = 0; n < 2; ++n) acc[a][b][m][n] = (f32x4){0.f, 0.f, 0.f, 0.f};
;         cur = nxt; cA = nA; cB = nB; ++ui;
.LBB0_204:
	s_ashr_i32 s17, s16, 31
	s_lshl_b64 s[22:23], s[16:17], 19
	v_readlane_b32 s52, v254, 28
	v_readlane_b32 s53, v254, 29
	s_add_u32 s22, s52, s22
	v_mov_b32_e32 v127, 0
	s_addc_u32 s23, s53, s23
	s_andn2_b64 vcc, exec, s[8:9]
	v_mov_b32_e32 v126, v127
	v_mov_b32_e32 v125, v127
	v_mov_b32_e32 v124, v127
	v_mov_b32_e32 v119, v127
	v_mov_b32_e32 v118, v127
	v_mov_b32_e32 v117, v127
	v_mov_b32_e32 v116, v127
	v_mov_b32_e32 v111, v127
	v_mov_b32_e32 v110, v127
	v_mov_b32_e32 v109, v127
	v_mov_b32_e32 v108, v127
	v_mov_b32_e32 v103, v127
	v_mov_b32_e32 v102, v127
	v_mov_b32_e32 v101, v127
	v_mov_b32_e32 v100, v127
	v_mov_b32_e32 v95, v127
	v_mov_b32_e32 v94, v127
	v_mov_b32_e32 v93, v127
	v_mov_b32_e32 v92, v127
	v_mov_b32_e32 v87, v127
	v_mov_b32_e32 v86, v127
	v_mov_b32_e32 v85, v127
	v_mov_b32_e32 v84, v127
	v_mov_b32_e32 v79, v127
	v_mov_b32_e32 v78, v127
	v_mov_b32_e32 v77, v127
	v_mov_b32_e32 v76, v127
	v_mov_b32_e32 v71, v127
	v_mov_b32_e32 v70, v127
	v_mov_b32_e32 v69, v127
	v_mov_b32_e32 v68, v127
	v_mov_b32_e32 v123, v127
	v_mov_b32_e32 v122, v127
	v_mov_b32_e32 v121, v127
	v_mov_b32_e32 v120, v127
	v_mov_b32_e32 v115, v127
	v_mov_b32_e32 v114, v127
	v_mov_b32_e32 v113, v127
	v_mov_b32_e32 v112, v127
	v_mov_b32_e32 v107, v127
	v_mov_b32_e32 v106, v127
	v_mov_b32_e32 v105, v127
	v_mov_b32_e32 v104, v127
	v_mov_b32_e32 v99, v127
	v_mov_b32_e32 v98, v127
	v_mov_b32_e32 v97, v127
	v_mov_b32_e32 v96, v127
	v_mov_b32_e32 v91, v127
	v_mov_b32_e32 v90, v127
	v_mov_b32_e32 v89, v127
	v_mov_b32_e32 v88, v127
	v_mov_b32_e32 v83, v127
	v_mov_b32_e32 v82, v127
	v_mov_b32_e32 v81, v127
	v_mov_b32_e32 v80, v127
	v_mov_b32_e32 v75, v127
	v_mov_b32_e32 v74, v127
	v_mov_b32_e32 v73, v127
	v_mov_b32_e32 v72, v127
	v_mov_b32_e32 v67, v127
	v_mov_b32_e32 v66, v127
	v_mov_b32_e32 v65, v127
	v_mov_b32_e32 v64, v127
	v_mov_b32_e32 v63, v127
	v_mov_b32_e32 v62, v127
	v_mov_b32_e32 v61, v127
	v_mov_b32_e32 v60, v127
	v_mov_b32_e32 v55, v127
	v_mov_b32_e32 v54, v127
	v_mov_b32_e32 v53, v127
	v_mov_b32_e32 v52, v127
	v_mov_b32_e32 v47, v127
	v_mov_b32_e32 v46, v127
	v_mov_b32_e32 v45, v127
	v_mov_b32_e32 v44, v127
	v_mov_b32_e32 v39, v127
	v_mov_b32_e32 v38, v127
	v_mov_b32_e32 v37, v127
	v_mov_b32_e32 v36, v127
	v_mov_b32_e32 v31, v127
	v_mov_b32_e32 v30, v127
	v_mov_b32_e32 v29, v127
	v_mov_b32_e32 v28, v127
	v_mov_b32_e32 v23, v127
	v_mov_b32_e32 v22, v127
	v_mov_b32_e32 v21, v127
	v_mov_b32_e32 v20, v127
	v_mov_b32_e32 v15, v127
	v_mov_b32_e32 v14, v127
	v_mov_b32_e32 v13, v127
	v_mov_b32_e32 v12, v127
	v_mov_b32_e32 v7, v127
	v_mov_b32_e32 v6, v127
	v_mov_b32_e32 v5, v127
	v_mov_b32_e32 v4, v127
	v_mov_b32_e32 v59, v127
	v_mov_b32_e32 v58, v127
	v_mov_b32_e32 v57, v127
	v_mov_b32_e32 v56, v127
	v_mov_b32_e32 v51, v127
	v_mov_b32_e32 v50, v127
	v_mov_b32_e32 v49, v127
	v_mov_b32_e32 v48, v127
	v_mov_b32_e32 v43, v127
	v_mov_b32_e32 v42, v127
	v_mov_b32_e32 v41, v127
	v_mov_b32_e32 v40, v127
	v_mov_b32_e32 v35, v127
	v_mov_b32_e32 v34, v127
	v_mov_b32_e32 v33, v127
	v_mov_b32_e32 v32, v127
	v_mov_b32_e32 v27, v127
	v_mov_b32_e32 v26, v127
	v_mov_b32_e32 v25, v127
	v_mov_b32_e32 v24, v127
	v_mov_b32_e32 v19, v127
	v_mov_b32_e32 v18, v127
	v_mov_b32_e32 v17, v127
	v_mov_b32_e32 v16, v127
	v_mov_b32_e32 v11, v127
	v_mov_b32_e32 v10, v127
	v_mov_b32_e32 v9, v127
	v_mov_b32_e32 v8, v127
	v_mov_b32_e32 v3, v127
	v_mov_b32_e32 v2, v127
	v_mov_b32_e32 v1, v127
	v_mov_b32_e32 v0, v127
	s_cbranch_vccnz .LBB0_207
	s_and_b64 s[12:13], s[12:13], exec
	s_cselect_b32 s17, s23, s29
	s_cselect_b32 s52, s22, s28
	s_add_u32 s12, s28, 0x40080
	s_addc_u32 s13, s29, 0
	s_add_u32 s28, s26, 0x100
	v_mov_b32_e32 v0, 0
	s_addc_u32 s29, s27, 0
	s_mov_b32 s26, 0
	v_mov_b32_e32 v1, v0
	v_mov_b32_e32 v2, v0
	v_mov_b32_e32 v3, v0
	v_mov_b32_e32 v8, v0
	v_mov_b32_e32 v9, v0
	v_mov_b32_e32 v10, v0
	v_mov_b32_e32 v11, v0
	v_mov_b32_e32 v16, v0
	v_mov_b32_e32 v17, v0
	v_mov_b32_e32 v18, v0
	v_mov_b32_e32 v19, v0
	v_mov_b32_e32 v24, v0
	v_mov_b32_e32 v25, v0
	v_mov_b32_e32 v26, v0
	v_mov_b32_e32 v27, v0
	v_mov_b32_e32 v32, v0
	v_mov_b32_e32 v33, v0
	v_mov_b32_e32 v34, v0
	v_mov_b32_e32 v35, v0
	v_mov_b32_e32 v40, v0
	v_mov_b32_e32 v41, v0
	v_mov_b32_e32 v42, v0
	v_mov_b32_e32 v43, v0
	v_mov_b32_e32 v48, v0
	v_mov_b32_e32 v49, v0
	v_mov_b32_e32 v50, v0
	v_mov_b32_e32 v51, v0
	v_mov_b32_e32 v56, v0
	v_mov_b32_e32 v57, v0
	v_mov_b32_e32 v58, v0
	v_mov_b32_e32 v59, v0
	v_mov_b32_e32 v4, v0
	v_mov_b32_e32 v5, v0
	v_mov_b32_e32 v6, v0
	v_mov_b32_e32 v7, v0
	v_mov_b32_e32 v12, v0
	v_mov_b32_e32 v13, v0
	v_mov_b32_e32 v14, v0
	v_mov_b32_e32 v15, v0
	v_mov_b32_e32 v20, v0
	v_mov_b32_e32 v21, v0
	v_mov_b32_e32 v22, v0
	v_mov_b32_e32 v23, v0
	v_mov_b32_e32 v28, v0
	v_mov_b32_e32 v29, v0
	v_mov_b32_e32 v30, v0
	v_mov_b32_e32 v31, v0
	v_mov_b32_e32 v36, v0
	v_mov_b32_e32 v37, v0
	v_mov_b32_e32 v38, v0
	v_mov_b32_e32 v39, v0
	v_mov_b32_e32 v44, v0
	v_mov_b32_e32 v45, v0
	v_mov_b32_e32 v46, v0
	v_mov_b32_e32 v47, v0
	v_mov_b32_e32 v52, v0
	v_mov_b32_e32 v53, v0
	v_mov_b32_e32 v54, v0
	v_mov_b32_e32 v55, v0
	v_mov_b32_e32 v60, v0
	v_mov_b32_e32 v61, v0
	v_mov_b32_e32 v62, v0
	v_mov_b32_e32 v63, v0
	v_mov_b32_e32 v64, v0
	v_mov_b32_e32 v65, v0
	v_mov_b32_e32 v66, v0
	v_mov_b32_e32 v67, v0
	v_mov_b32_e32 v72, v0
	v_mov_b32_e32 v73, v0
	v_mov_b32_e32 v74, v0
	v_mov_b32_e32 v75, v0
	v_mov_b32_e32 v80, v0
	v_mov_b32_e32 v81, v0
	v_mov_b32_e32 v82, v0
	v_mov_b32_e32 v83, v0
	v_mov_b32_e32 v88, v0
	v_mov_b32_e32 v89, v0
	v_mov_b32_e32 v90, v0
	v_mov_b32_e32 v91, v0
	v_mov_b32_e32 v96, v0
	v_mov_b32_e32 v97, v0
	v_mov_b32_e32 v98, v0
	v_mov_b32_e32 v99, v0
	v_mov_b32_e32 v104, v0
	v_mov_b32_e32 v105, v0
	v_mov_b32_e32 v106, v0
	v_mov_b32_e32 v107, v0
	v_mov_b32_e32 v112, v0
	v_mov_b32_e32 v113, v0
	v_mov_b32_e32 v114, v0
	v_mov_b32_e32 v115, v0
	v_mov_b32_e32 v120, v0
	v_mov_b32_e32 v121, v0
	v_mov_b32_e32 v122, v0
	v_mov_b32_e32 v123, v0
	v_mov_b32_e32 v68, v0
	v_mov_b32_e32 v69, v0
	v_mov_b32_e32 v70, v0
	v_mov_b32_e32 v71, v0
	v_mov_b32_e32 v76, v0
	v_mov_b32_e32 v77, v0
	v_mov_b32_e32 v78, v0
	v_mov_b32_e32 v79, v0
	v_mov_b32_e32 v84, v0
	v_mov_b32_e32 v85, v0
	v_mov_b32_e32 v86, v0
	v_mov_b32_e32 v87, v0
	v_mov_b32_e32 v92, v0
	v_mov_b32_e32 v93, v0
	v_mov_b32_e32 v94, v0
	v_mov_b32_e32 v95, v0
	v_mov_b32_e32 v100, v0
	v_mov_b32_e32 v101, v0
	v_mov_b32_e32 v102, v0
	v_mov_b32_e32 v103, v0
	v_mov_b32_e32 v108, v0
	v_mov_b32_e32 v109, v0
	v_mov_b32_e32 v110, v0
	v_mov_b32_e32 v111, v0
	v_mov_b32_e32 v116, v0
	v_mov_b32_e32 v117, v0
	v_mov_b32_e32 v118, v0
	v_mov_b32_e32 v119, v0
	v_mov_b32_e32 v124, v0
	v_mov_b32_e32 v125, v0
	v_mov_b32_e32 v126, v0
	v_mov_b32_e32 v127, v0
	s_mov_b64 s[58:59], 0x80
	.p2align	6

; #define LAS __attribute__((address_space(3)))
;     ...
;         const bool has_next = S.next(ui + 1, nxt);
;         const unsigned rsoff = (unsigned)STAGE_BYTES + (unsigned)(ui & 1) * 1024u;
;         if constexpr (Epi::NEEDS_RS) { if (wid < 4) __builtin_amdgcn_global_load_lds((const unsigned*)(E.rsv + cur.pm * 256 + wid * 64 + lane), (LAS unsigned*)(lds + rsoff + wid * 256), 4, 0, 0); }
;         const char* nA = has_next ? (const char*)g.A + (size_t)nxt.pm * tstepA + (size_t)nxt.pn * APN : cA; const char* nB = has_next ? (const char*)g.Bt + (size_t)nxt.pn * tstepB : cB;
;         for (int t = 0; t < nt; t += 2) {
;             const bool last = (t == nt - 2);
;             const char* a1 = cA + (size_t)(t + 1) * kstep;
;             const char* a2 = last ? nA : cA + (size_t)(t + 2) * kstep; const char* b2 = last ? nB : cB + (size_t)(t + 2) * kstep;
;             const char* a3 = a2 + kstep; const char* b3 = b2 + kstep;
;     ...
; #pragma unroll
;         for (int a = 0; a < 2; ++a)
; #pragma unroll
;             for (int b = 0; b < 2; ++b)
; #pragma unroll
;                 for (int m = 0; m < 4; ++m)
; #pragma unroll
;                     for (int n = 0; n < 2; ++n) acc[a][b][m][n] = (f32x4){0.f, 0.f, 0.f, 0.f};
;         cur = nxt; cA = nA; cB = nB; ++ui;
.LBB0_283:
	s_ashr_i32 s19, s18, 31
	s_lshl_b64 s[24:25], s[18:19], 18
	s_add_u32 s19, s38, s24
	s_addc_u32 s53, s39, s25
	s_lshl_b64 s[24:25], s[16:17], 8
	s_add_u32 s24, s19, s24
	v_mov_b32_e32 v131, 0
	s_addc_u32 s25, s53, s25
	s_andn2_b64 vcc, exec, s[4:5]
	v_mov_b32_e32 v130, v131
	v_mov_b32_e32 v129, v131
	v_mov_b32_e32 v128, v131
	v_mov_b32_e32 v135, v131
	v_mov_b32_e32 v134, v131
	v_mov_b32_e32 v133, v131
	v_mov_b32_e32 v132, v131
	v_mov_b32_e32 v127, v131
	v_mov_b32_e32 v126, v131
	v_mov_b32_e32 v125, v131
	v_mov_b32_e32 v124, v131
	v_mov_b32_e32 v123, v131
	v_mov_b32_e32 v122, v131
	v_mov_b32_e32 v121, v131
	v_mov_b32_e32 v120, v131
	v_mov_b32_e32 v111, v131
	v_mov_b32_e32 v110, v131
	v_mov_b32_e32 v109, v131
	v_mov_b32_e32 v108, v131
	v_mov_b32_e32 v107, v131
	v_mov_b32_e32 v106, v131
	v_mov_b32_e32 v105, v131
	v_mov_b32_e32 v104, v131
	v_mov_b32_e32 v103, v131
	v_mov_b32_e32 v102, v131
	v_mov_b32_e32 v101, v131
	v_mov_b32_e32 v100, v131
	v_mov_b32_e32 v99, v131
	v_mov_b32_e32 v98, v131
	v_mov_b32_e32 v97, v131
	v_mov_b32_e32 v96, v131
	v_mov_b32_e32 v63, v131
	v_mov_b32_e32 v62, v131
	v_mov_b32_e32 v61, v131
	v_mov_b32_e32 v60, v131
	v_mov_b32_e32 v59, v131
	v_mov_b32_e32 v58, v131
	v_mov_b32_e32 v57, v131
	v_mov_b32_e32 v56, v131
	v_mov_b32_e32 v55, v131
	v_mov_b32_e32 v54, v131
	v_mov_b32_e32 v53, v131
	v_mov_b32_e32 v52, v131
	v_mov_b32_e32 v51, v131
	v_mov_b32_e32 v50, v131
	v_mov_b32_e32 v49, v131
	v_mov_b32_e32 v48, v131
	v_mov_b32_e32 v47, v131
	v_mov_b32_e32 v46, v131
	v_mov_b32_e32 v45, v131
	v_mov_b32_e32 v44, v131
	v_mov_b32_e32 v43, v131
	v_mov_b32_e32 v42, v131
	v_mov_b32_e32 v41, v131
	v_mov_b32_e32 v40, v131
	v_mov_b32_e32 v39, v131
	v_mov_b32_e32 v38, v131
	v_mov_b32_e32 v37, v131
	v_mov_b32_e32 v36, v131
	v_mov_b32_e32 v35, v131
	v_mov_b32_e32 v34, v131
	v_mov_b32_e32 v33, v131
	v_mov_b32_e32 v32, v131
	v_mov_b32_e32 v95, v131
	v_mov_b32_e32 v94, v131
	v_mov_b32_e32 v93, v131
	v_mov_b32_e32 v92, v131
	v_mov_b32_e32 v91, v131
	v_mov_b32_e32 v90, v131
	v_mov_b32_e32 v89, v131
	v_mov_b32_e32 v88, v131
	v_mov_b32_e32 v87, v131
	v_mov_b32_e32 v86, v131
	v_mov_b32_e32 v85, v131
	v_mov_b32_e32 v84, v131
	v_mov_b32_e32 v83, v131
	v_mov_b32_e32 v82, v131
	v_mov_b32_e32 v81, v131
	v_mov_b32_e32 v80, v131
	v_mov_b32_e32 v79, v131
	v_mov_b32_e32 v78, v131
	v_mov_b32_e32 v77, v131
	v_mov_b32_e32 v76, v131
	v_mov_b32_e32 v75, v131
	v_mov_b32_e32 v74, v131
	v_mov_b32_e32 v73, v131
	v_mov_b32_e32 v72, v131
	v_mov_b32_e32 v71, v131
	v_mov_b32_e32 v70, v131
	v_mov_b32_e32 v69, v131
	v_mov_b32_e32 v68, v131
	v_mov_b32_e32 v67, v131
	v_mov_b32_e32 v66, v131
	v_mov_b32_e32 v65, v131
	v_mov_b32_e32 v64, v131
	v_mov_b32_e32 v31, v131
	v_mov_b32_e32 v30, v131
	v_mov_b32_e32 v29, v131
	v_mov_b32_e32 v28, v131
	v_mov_b32_e32 v27, v131
	v_mov_b32_e32 v26, v131
	v_mov_b32_e32 v25, v131
	v_mov_b32_e32 v24, v131
	v_mov_b32_e32 v23, v131
	v_mov_b32_e32 v22, v131
	v_mov_b32_e32 v21, v131
	v_mov_b32_e32 v20, v131
	v_mov_b32_e32 v19, v131
	v_mov_b32_e32 v18, v131
	v_mov_b32_e32 v17, v131
	v_mov_b32_e32 v16, v131
	v_mov_b32_e32 v15, v131
	v_mov_b32_e32 v14, v131
	v_mov_b32_e32 v13, v131
	v_mov_b32_e32 v12, v131
	v_mov_b32_e32 v11, v131
	v_mov_b32_e32 v10, v131
	v_mov_b32_e32 v9, v131
	v_mov_b32_e32 v8, v131
	v_mov_b32_e32 v7, v131
	v_mov_b32_e32 v6, v131
	v_mov_b32_e32 v5, v131
	v_mov_b32_e32 v4, v131
	v_mov_b32_e32 v3, v131
	v_mov_b32_e32 v2, v131
	v_mov_b32_e32 v1, v131
	v_mov_b32_e32 v0, v131
	s_cbranch_vccnz .LBB0_286
	s_and_b64 s[12:13], s[12:13], exec
	s_cselect_b32 s17, s25, s31
	s_cselect_b32 s19, s24, s30
	s_add_u32 s12, s30, 0x20080
	s_addc_u32 s13, s31, 0
	s_add_u32 s30, s28, 0x100
	v_mov_b32_e32 v0, 0
	s_addc_u32 s31, s29, 0
	s_mov_b32 s28, 0
	v_mov_b32_e32 v1, v0
	v_mov_b32_e32 v2, v0
	v_mov_b32_e32 v3, v0
	v_mov_b32_e32 v4, v0
	v_mov_b32_e32 v5, v0
	v_mov_b32_e32 v6, v0
	v_mov_b32_e32 v7, v0
	v_mov_b32_e32 v8, v0
	v_mov_b32_e32 v9, v0
	v_mov_b32_e32 v10, v0
	v_mov_b32_e32 v11, v0
	v_mov_b32_e32 v12, v0
	v_mov_b32_e32 v13, v0
	v_mov_b32_e32 v14, v0
	v_mov_b32_e32 v15, v0
	v_mov_b32_e32 v16, v0
	v_mov_b32_e32 v17, v0
	v_mov_b32_e32 v18, v0
	v_mov_b32_e32 v19, v0
	v_mov_b32_e32 v20, v0
	v_mov_b32_e32 v21, v0
	v_mov_b32_e32 v22, v0
	v_mov_b32_e32 v23, v0
	v_mov_b32_e32 v24, v0
	v_mov_b32_e32 v25, v0
	v_mov_b32_e32 v26, v0
	v_mov_b32_e32 v27, v0
	v_mov_b32_e32 v28, v0
	v_mov_b32_e32 v29, v0
	v_mov_b32_e32 v30, v0
	v_mov_b32_e32 v31, v0
	v_mov_b32_e32 v64, v0
	v_mov_b32_e32 v65, v0
	v_mov_b32_e32 v66, v0
	v_mov_b32_e32 v67, v0
	v_mov_b32_e32 v68, v0
	v_mov_b32_e32 v69, v0
	v_mov_b32_e32 v70, v0
	v_mov_b32_e32 v71, v0
	v_mov_b32_e32 v72, v0
	v_mov_b32_e32 v73, v0
	v_mov_b32_e32 v74, v0
	v_mov_b32_e32 v75, v0
	v_mov_b32_e32 v76, v0
	v_mov_b32_e32 v77, v0
	v_mov_b32_e32 v78, v0
	v_mov_b32_e32 v79, v0
	v_mov_b32_e32 v80, v0
	v_mov_b32_e32 v81, v0
	v_mov_b32_e32 v82, v0
	v_mov_b32_e32 v83, v0
	v_mov_b32_e32 v84, v0
	v_mov_b32_e32 v85, v0
	v_mov_b32_e32 v86, v0
	v_mov_b32_e32 v87, v0
	v_mov_b32_e32 v88, v0
	v_mov_b32_e32 v89, v0
	v_mov_b32_e32 v90, v0
	v_mov_b32_e32 v91, v0
	v_mov_b32_e32 v92, v0
	v_mov_b32_e32 v93, v0
	v_mov_b32_e32 v94, v0
	v_mov_b32_e32 v95, v0
	v_mov_b32_e32 v32, v0
	v_mov_b32_e32 v33, v0
	v_mov_b32_e32 v34, v0
	v_mov_b32_e32 v35, v0
	v_mov_b32_e32 v36, v0
	v_mov_b32_e32 v37, v0
	v_mov_b32_e32 v38, v0
	v_mov_b32_e32 v39, v0
	v_mov_b32_e32 v40, v0
	v_mov_b32_e32 v41, v0
	v_mov_b32_e32 v42, v0
	v_mov_b32_e32 v43, v0
	v_mov_b32_e32 v44, v0
	v_mov_b32_e32 v45, v0
	v_mov_b32_e32 v46, v0
	v_mov_b32_e32 v47, v0
	v_mov_b32_e32 v48, v0
	v_mov_b32_e32 v49, v0
	v_mov_b32_e32 v50, v0
	v_mov_b32_e32 v51, v0
	v_mov_b32_e32 v52, v0
	v_mov_b32_e32 v53, v0
	v_mov_b32_e32 v54, v0
	v_mov_b32_e32 v55, v0
	v_mov_b32_e32 v56, v0
	v_mov_b32_e32 v57, v0
	v_mov_b32_e32 v58, v0
	v_mov_b32_e32 v59, v0
	v_mov_b32_e32 v60, v0
	v_mov_b32_e32 v61, v0
	v_mov_b32_e32 v62, v0
	v_mov_b32_e32 v63, v0
	v_mov_b32_e32 v96, v0
	v_mov_b32_e32 v97, v0
	v_mov_b32_e32 v98, v0
	v_mov_b32_e32 v99, v0
	v_mov_b32_e32 v100, v0
	v_mov_b32_e32 v101, v0
	v_mov_b32_e32 v102, v0
	v_mov_b32_e32 v103, v0
	v_mov_b32_e32 v104, v0
	v_mov_b32_e32 v105, v0
	v_mov_b32_e32 v106, v0
	v_mov_b32_e32 v107, v0
	v_mov_b32_e32 v108, v0
	v_mov_b32_e32 v109, v0
	v_mov_b32_e32 v110, v0
	v_mov_b32_e32 v111, v0
	v_mov_b32_e32 v120, v0
	v_mov_b32_e32 v121, v0
	v_mov_b32_e32 v122, v0
	v_mov_b32_e32 v123, v0
	v_mov_b32_e32 v124, v0
	v_mov_b32_e32 v125, v0
	v_mov_b32_e32 v126, v0
	v_mov_b32_e32 v127, v0
	v_mov_b32_e32 v132, v0
	v_mov_b32_e32 v133, v0
	v_mov_b32_e32 v134, v0
	v_mov_b32_e32 v135, v0
	v_mov_b32_e32 v128, v0
	v_mov_b32_e32 v129, v0
	v_mov_b32_e32 v130, v0
	v_mov_b32_e32 v131, v0
	s_mov_b64 s[58:59], 0x80
	.p2align	6

; #define LAS __attribute__((address_space(3)))
;     ...
;         const bool has_next = S.next(ui + 1, nxt);
;         const unsigned rsoff = (unsigned)STAGE_BYTES + (unsigned)(ui & 1) * 1024u;
;         if constexpr (Epi::NEEDS_RS) { if (wid < 4) __builtin_amdgcn_global_load_lds((const unsigned*)(E.rsv + cur.pm * 256 + wid * 64 + lane), (LAS unsigned*)(lds + rsoff + wid * 256), 4, 0, 0); }
;         const char* nA = has_next ? (const char*)g.A + (size_t)nxt.pm * tstepA + (size_t)nxt.pn * APN : cA; const char* nB = has_next ? (const char*)g.Bt + (size_t)nxt.pn * tstepB : cB;
;         for (int t = 0; t < nt; t += 2) {
;             const bool last = (t == nt - 2);
;             const char* a1 = cA + (size_t)(t + 1) * kstep;
;             const char* a2 = last ? nA : cA + (size_t)(t + 2) * kstep; const char* b2 = last ? nB : cB + (size_t)(t + 2) * kstep;
;             const char* a3 = a2 + kstep; const char* b3 = b2 + kstep;
;     ...
; #pragma unroll
;         for (int a = 0; a < 2; ++a)
; #pragma unroll
;             for (int b = 0; b < 2; ++b)
; #pragma unroll
;                 for (int m = 0; m < 4; ++m)
; #pragma unroll
;                     for (int n = 0; n < 2; ++n) acc[a][b][m][n] = (f32x4){0.f, 0.f, 0.f, 0.f};
;         cur = nxt; cA = nA; cB = nB; ++ui;
.LBB0_312:
	v_mov_b32_e32 v127, 0
	s_andn2_b64 vcc, exec, s[22:23]
	v_mov_b32_e32 v126, v127
	v_mov_b32_e32 v125, v127
	v_mov_b32_e32 v124, v127
	v_mov_b32_e32 v123, v127
	v_mov_b32_e32 v122, v127
	v_mov_b32_e32 v121, v127
	v_mov_b32_e32 v120, v127
	v_mov_b32_e32 v111, v127
	v_mov_b32_e32 v110, v127
	v_mov_b32_e32 v109, v127
	v_mov_b32_e32 v108, v127
	v_mov_b32_e32 v107, v127
	v_mov_b32_e32 v106, v127
	v_mov_b32_e32 v105, v127
	v_mov_b32_e32 v104, v127
	v_mov_b32_e32 v95, v127
	v_mov_b32_e32 v94, v127
	v_mov_b32_e32 v93, v127
	v_mov_b32_e32 v92, v127
	v_mov_b32_e32 v91, v127
	v_mov_b32_e32 v90, v127
	v_mov_b32_e32 v89, v127
	v_mov_b32_e32 v88, v127
	v_mov_b32_e32 v79, v127
	v_mov_b32_e32 v78, v127
	v_mov_b32_e32 v77, v127
	v_mov_b32_e32 v76, v127
	v_mov_b32_e32 v75, v127
	v_mov_b32_e32 v74, v127
	v_mov_b32_e32 v73, v127
	v_mov_b32_e32 v72, v127
	v_mov_b32_e32 v119, v127
	v_mov_b32_e32 v118, v127
	v_mov_b32_e32 v117, v127
	v_mov_b32_e32 v116, v127
	v_mov_b32_e32 v115, v127
	v_mov_b32_e32 v114, v127
	v_mov_b32_e32 v113, v127
	v_mov_b32_e32 v112, v127
	v_mov_b32_e32 v103, v127
	v_mov_b32_e32 v102, v127
	v_mov_b32_e32 v101, v127
	v_mov_b32_e32 v100, v127
	v_mov_b32_e32 v99, v127
	v_mov_b32_e32 v98, v127
	v_mov_b32_e32 v97, v127
	v_mov_b32_e32 v96, v127
	v_mov_b32_e32 v87, v127
	v_mov_b32_e32 v86, v127
	v_mov_b32_e32 v85, v127
	v_mov_b32_e32 v84, v127
	v_mov_b32_e32 v83, v127
	v_mov_b32_e32 v82, v127
	v_mov_b32_e32 v81, v127
	v_mov_b32_e32 v80, v127
	v_mov_b32_e32 v71, v127
	v_mov_b32_e32 v70, v127
	v_mov_b32_e32 v69, v127
	v_mov_b32_e32 v68, v127
	v_mov_b32_e32 v67, v127
	v_mov_b32_e32 v66, v127
	v_mov_b32_e32 v65, v127
	v_mov_b32_e32 v64, v127
	v_mov_b32_e32 v63, v127
	v_mov_b32_e32 v62, v127
	v_mov_b32_e32 v61, v127
	v_mov_b32_e32 v60, v127
	v_mov_b32_e32 v59, v127
	v_mov_b32_e32 v58, v127
	v_mov_b32_e32 v57, v127
	v_mov_b32_e32 v56, v127
	v_mov_b32_e32 v47, v127
	v_mov_b32_e32 v46, v127
	v_mov_b32_e32 v45, v127
	v_mov_b32_e32 v44, v127
	v_mov_b32_e32 v43, v127
	v_mov_b32_e32 v42, v127
	v_mov_b32_e32 v41, v127
	v_mov_b32_e32 v40, v127
	v_mov_b32_e32 v31, v127
	v_mov_b32_e32 v30, v127
	v_mov_b32_e32 v29, v127
	v_mov_b32_e32 v28, v127
	v_mov_b32_e32 v27, v127
	v_mov_b32_e32 v26, v127
	v_mov_b32_e32 v25, v127
	v_mov_b32_e32 v24, v127
	v_mov_b32_e32 v15, v127
	v_mov_b32_e32 v14, v127
	v_mov_b32_e32 v13, v127
	v_mov_b32_e32 v12, v127
	v_mov_b32_e32 v11, v127
	v_mov_b32_e32 v10, v127
	v_mov_b32_e32 v9, v127
	v_mov_b32_e32 v8, v127
	v_mov_b32_e32 v55, v127
	v_mov_b32_e32 v54, v127
	v_mov_b32_e32 v53, v127
	v_mov_b32_e32 v52, v127
	v_mov_b32_e32 v51, v127
	v_mov_b32_e32 v50, v127
	v_mov_b32_e32 v49, v127
	v_mov_b32_e32 v48, v127
	v_mov_b32_e32 v39, v127
	v_mov_b32_e32 v38, v127
	v_mov_b32_e32 v37, v127
	v_mov_b32_e32 v36, v127
	v_mov_b32_e32 v35, v127
	v_mov_b32_e32 v34, v127
	v_mov_b32_e32 v33, v127
	v_mov_b32_e32 v32, v127
	v_mov_b32_e32 v23, v127
	v_mov_b32_e32 v22, v127
	v_mov_b32_e32 v21, v127
	v_mov_b32_e32 v20, v127
	v_mov_b32_e32 v19, v127
	v_mov_b32_e32 v18, v127
	v_mov_b32_e32 v17, v127
	v_mov_b32_e32 v16, v127
	v_mov_b32_e32 v7, v127
	v_mov_b32_e32 v6, v127
	v_mov_b32_e32 v5, v127
	v_mov_b32_e32 v4, v127
	v_mov_b32_e32 v3, v127
	v_mov_b32_e32 v2, v127
	v_mov_b32_e32 v1, v127
	v_mov_b32_e32 v0, v127
	s_cbranch_vccnz .LBB0_315
	s_add_u32 s48, s2, 0x100
	v_mov_b32_e32 v0, 0
	s_addc_u32 s49, s3, 0
	s_mov_b32 s4, 0
	v_mov_b32_e32 v1, v0
	v_mov_b32_e32 v2, v0
	v_mov_b32_e32 v3, v0
	v_mov_b32_e32 v4, v0
	v_mov_b32_e32 v5, v0
	v_mov_b32_e32 v6, v0
	v_mov_b32_e32 v7, v0
	v_mov_b32_e32 v16, v0
	v_mov_b32_e32 v17, v0
	v_mov_b32_e32 v18, v0
	v_mov_b32_e32 v19, v0
	v_mov_b32_e32 v20, v0
	v_mov_b32_e32 v21, v0
	v_mov_b32_e32 v22, v0
	v_mov_b32_e32 v23, v0
	v_mov_b32_e32 v32, v0
	v_mov_b32_e32 v33, v0
	v_mov_b32_e32 v34, v0
	v_mov_b32_e32 v35, v0
	v_mov_b32_e32 v36, v0
	v_mov_b32_e32 v37, v0
	v_mov_b32_e32 v38, v0
	v_mov_b32_e32 v39, v0
	v_mov_b32_e32 v48, v0
	v_mov_b32_e32 v49, v0
	v_mov_b32_e32 v50, v0
	v_mov_b32_e32 v51, v0
	v_mov_b32_e32 v52, v0
	v_mov_b32_e32 v53, v0
	v_mov_b32_e32 v54, v0
	v_mov_b32_e32 v55, v0
	v_mov_b32_e32 v8, v0
	v_mov_b32_e32 v9, v0
	v_mov_b32_e32 v10, v0
	v_mov_b32_e32 v11, v0
	v_mov_b32_e32 v12, v0
	v_mov_b32_e32 v13, v0
	v_mov_b32_e32 v14, v0
	v_mov_b32_e32 v15, v0
	v_mov_b32_e32 v24, v0
	v_mov_b32_e32 v25, v0
	v_mov_b32_e32 v26, v0
	v_mov_b32_e32 v27, v0
	v_mov_b32_e32 v28, v0
	v_mov_b32_e32 v29, v0
	v_mov_b32_e32 v30, v0
	v_mov_b32_e32 v31, v0
	v_mov_b32_e32 v40, v0
	v_mov_b32_e32 v41, v0
	v_mov_b32_e32 v42, v0
	v_mov_b32_e32 v43, v0
	v_mov_b32_e32 v44, v0
	v_mov_b32_e32 v45, v0
	v_mov_b32_e32 v46, v0
	v_mov_b32_e32 v47, v0
	v_mov_b32_e32 v56, v0
	v_mov_b32_e32 v57, v0
	v_mov_b32_e32 v58, v0
	v_mov_b32_e32 v59, v0
	v_mov_b32_e32 v60, v0
	v_mov_b32_e32 v61, v0
	v_mov_b32_e32 v62, v0
	v_mov_b32_e32 v63, v0
	v_mov_b32_e32 v64, v0
	v_mov_b32_e32 v65, v0
	v_mov_b32_e32 v66, v0
	v_mov_b32_e32 v67, v0
	v_mov_b32_e32 v68, v0
	v_mov_b32_e32 v69, v0
	v_mov_b32_e32 v70, v0
	v_mov_b32_e32 v71, v0
	v_mov_b32_e32 v80, v0
	v_mov_b32_e32 v81, v0
	v_mov_b32_e32 v82, v0
	v_mov_b32_e32 v83, v0
	v_mov_b32_e32 v84, v0
	v_mov_b32_e32 v85, v0
	v_mov_b32_e32 v86, v0
	v_mov_b32_e32 v87, v0
	v_mov_b32_e32 v96, v0
	v_mov_b32_e32 v97, v0
	v_mov_b32_e32 v98, v0
	v_mov_b32_e32 v99, v0
	v_mov_b32_e32 v100, v0
	v_mov_b32_e32 v101, v0
	v_mov_b32_e32 v102, v0
	v_mov_b32_e32 v103, v0
	v_mov_b32_e32 v112, v0
	v_mov_b32_e32 v113, v0
	v_mov_b32_e32 v114, v0
	v_mov_b32_e32 v115, v0
	v_mov_b32_e32 v116, v0
	v_mov_b32_e32 v117, v0
	v_mov_b32_e32 v118, v0
	v_mov_b32_e32 v119, v0
	v_mov_b32_e32 v72, v0
	v_mov_b32_e32 v73, v0
	v_mov_b32_e32 v74, v0
	v_mov_b32_e32 v75, v0
	v_mov_b32_e32 v76, v0
	v_mov_b32_e32 v77, v0
	v_mov_b32_e32 v78, v0
	v_mov_b32_e32 v79, v0
	v_mov_b32_e32 v88, v0
	v_mov_b32_e32 v89, v0
	v_mov_b32_e32 v90, v0
	v_mov_b32_e32 v91, v0
	v_mov_b32_e32 v92, v0
	v_mov_b32_e32 v93, v0
	v_mov_b32_e32 v94, v0
	v_mov_b32_e32 v95, v0
	v_mov_b32_e32 v104, v0
	v_mov_b32_e32 v105, v0
	v_mov_b32_e32 v106, v0
	v_mov_b32_e32 v107, v0
	v_mov_b32_e32 v108, v0
	v_mov_b32_e32 v109, v0
	v_mov_b32_e32 v110, v0
	v_mov_b32_e32 v111, v0
	v_mov_b32_e32 v120, v0
	v_mov_b32_e32 v121, v0
	v_mov_b32_e32 v122, v0
	v_mov_b32_e32 v123, v0
	v_mov_b32_e32 v124, v0
	v_mov_b32_e32 v125, v0
	v_mov_b32_e32 v126, v0
	v_mov_b32_e32 v127, v0
	s_mov_b64 s[56:57], 0x80
	.p2align	6

; #define LAS __attribute__((address_space(3)))
;     ...
;         const bool has_next = S.next(ui + 1, nxt);
;         const unsigned rsoff = (unsigned)STAGE_BYTES + (unsigned)(ui & 1) * 1024u;
;         if constexpr (Epi::NEEDS_RS) { if (wid < 4) __builtin_amdgcn_global_load_lds((const unsigned*)(E.rsv + cur.pm * 256 + wid * 64 + lane), (LAS unsigned*)(lds + rsoff + wid * 256), 4, 0, 0); }
;         const char* nA = has_next ? (const char*)g.A + (size_t)nxt.pm * tstepA + (size_t)nxt.pn * APN : cA; const char* nB = has_next ? (const char*)g.Bt + (size_t)nxt.pn * tstepB : cB;
;         for (int t = 0; t < nt; t += 2) {
;             const bool last = (t == nt - 2);
;             const char* a1 = cA + (size_t)(t + 1) * kstep;
;             const char* a2 = last ? nA : cA + (size_t)(t + 2) * kstep; const char* b2 = last ? nB : cB + (size_t)(t + 2) * kstep;
;             const char* a3 = a2 + kstep; const char* b3 = b2 + kstep;
;     ...
; #pragma unroll
;         for (int a = 0; a < 2; ++a)
; #pragma unroll
;             for (int b = 0; b < 2; ++b)
; #pragma unroll
;                 for (int m = 0; m < 4; ++m)
; #pragma unroll
;                     for (int n = 0; n < 2; ++n) acc[a][b][m][n] = (f32x4){0.f, 0.f, 0.f, 0.f};
;         cur = nxt; cA = nA; cB = nB; ++ui;
.LBB0_343:
	s_ashr_i32 s17, s16, 31
	s_lshl_b64 s[22:23], s[16:17], 19
	v_readlane_b32 s52, v254, 28
	v_readlane_b32 s53, v254, 29
	s_add_u32 s22, s52, s22
	v_mov_b32_e32 v127, 0
	s_addc_u32 s23, s53, s23
	s_andn2_b64 vcc, exec, s[8:9]
	v_mov_b32_e32 v126, v127
	v_mov_b32_e32 v125, v127
	v_mov_b32_e32 v124, v127
	v_mov_b32_e32 v123, v127
	v_mov_b32_e32 v122, v127
	v_mov_b32_e32 v121, v127
	v_mov_b32_e32 v120, v127
	v_mov_b32_e32 v111, v127
	v_mov_b32_e32 v110, v127
	v_mov_b32_e32 v109, v127
	v_mov_b32_e32 v108, v127
	v_mov_b32_e32 v107, v127
	v_mov_b32_e32 v106, v127
	v_mov_b32_e32 v105, v127
	v_mov_b32_e32 v104, v127
	v_mov_b32_e32 v95, v127
	v_mov_b32_e32 v94, v127
	v_mov_b32_e32 v93, v127
	v_mov_b32_e32 v92, v127
	v_mov_b32_e32 v91, v127
	v_mov_b32_e32 v90, v127
	v_mov_b32_e32 v89, v127
	v_mov_b32_e32 v88, v127
	v_mov_b32_e32 v79, v127
	v_mov_b32_e32 v78, v127
	v_mov_b32_e32 v77, v127
	v_mov_b32_e32 v76, v127
	v_mov_b32_e32 v75, v127
	v_mov_b32_e32 v74, v127
	v_mov_b32_e32 v73, v127
	v_mov_b32_e32 v72, v127
	v_mov_b32_e32 v119, v127
	v_mov_b32_e32 v118, v127
	v_mov_b32_e32 v117, v127
	v_mov_b32_e32 v116, v127
	v_mov_b32_e32 v115, v127
	v_mov_b32_e32 v114, v127
	v_mov_b32_e32 v113, v127
	v_mov_b32_e32 v112, v127
	v_mov_b32_e32 v103, v127
	v_mov_b32_e32 v102, v127
	v_mov_b32_e32 v101, v127
	v_mov_b32_e32 v100, v127
	v_mov_b32_e32 v99, v127
	v_mov_b32_e32 v98, v127
	v_mov_b32_e32 v97, v127
	v_mov_b32_e32 v96, v127
	v_mov_b32_e32 v87, v127
	v_mov_b32_e32 v86, v127
	v_mov_b32_e32 v85, v127
	v_mov_b32_e32 v84, v127
	v_mov_b32_e32 v83, v127
	v_mov_b32_e32 v82, v127
	v_mov_b32_e32 v81, v127
	v_mov_b32_e32 v80, v127
	v_mov_b32_e32 v71, v127
	v_mov_b32_e32 v70, v127
	v_mov_b32_e32 v69, v127
	v_mov_b32_e32 v68, v127
	v_mov_b32_e32 v67, v127
	v_mov_b32_e32 v66, v127
	v_mov_b32_e32 v65, v127
	v_mov_b32_e32 v64, v127
	v_mov_b32_e32 v63, v127
	v_mov_b32_e32 v62, v127
	v_mov_b32_e32 v61, v127
	v_mov_b32_e32 v60, v127
	v_mov_b32_e32 v59, v127
	v_mov_b32_e32 v58, v127
	v_mov_b32_e32 v57, v127
	v_mov_b32_e32 v56, v127
	v_mov_b32_e32 v47, v127
	v_mov_b32_e32 v46, v127
	v_mov_b32_e32 v45, v127
	v_mov_b32_e32 v44, v127
	v_mov_b32_e32 v43, v127
	v_mov_b32_e32 v42, v127
	v_mov_b32_e32 v41, v127
	v_mov_b32_e32 v40, v127
	v_mov_b32_e32 v31, v127
	v_mov_b32_e32 v30, v127
	v_mov_b32_e32 v29, v127
	v_mov_b32_e32 v28, v127
	v_mov_b32_e32 v27, v127
	v_mov_b32_e32 v26, v127
	v_mov_b32_e32 v25, v127
	v_mov_b32_e32 v24, v127
	v_mov_b32_e32 v15, v127
	v_mov_b32_e32 v14, v127
	v_mov_b32_e32 v13, v127
	v_mov_b32_e32 v12, v127
	v_mov_b32_e32 v11, v127
	v_mov_b32_e32 v10, v127
	v_mov_b32_e32 v9, v127
	v_mov_b32_e32 v8, v127
	v_mov_b32_e32 v55, v127
	v_mov_b32_e32 v54, v127
	v_mov_b32_e32 v53, v127
	v_mov_b32_e32 v52, v127
	v_mov_b32_e32 v51, v127
	v_mov_b32_e32 v50, v127
	v_mov_b32_e32 v49, v127
	v_mov_b32_e32 v48, v127
	v_mov_b32_e32 v39, v127
	v_mov_b32_e32 v38, v127
	v_mov_b32_e32 v37, v127
	v_mov_b32_e32 v36, v127
	v_mov_b32_e32 v35, v127
	v_mov_b32_e32 v34, v127
	v_mov_b32_e32 v33, v127
	v_mov_b32_e32 v32, v127
	v_mov_b32_e32 v23, v127
	v_mov_b32_e32 v22, v127
	v_mov_b32_e32 v21, v127
	v_mov_b32_e32 v20, v127
	v_mov_b32_e32 v19, v127
	v_mov_b32_e32 v18, v127
	v_mov_b32_e32 v17, v127
	v_mov_b32_e32 v16, v127
	v_mov_b32_e32 v7, v127
	v_mov_b32_e32 v6, v127
	v_mov_b32_e32 v5, v127
	v_mov_b32_e32 v4, v127
	v_mov_b32_e32 v3, v127
	v_mov_b32_e32 v2, v127
	v_mov_b32_e32 v1, v127
	v_mov_b32_e32 v0, v127
	s_cbranch_vccnz .LBB0_346
	s_and_b64 s[12:13], s[12:13], exec
	s_cselect_b32 s17, s23, s29
	s_cselect_b32 s52, s22, s28
	s_add_u32 s12, s28, 0x40080
	s_addc_u32 s13, s29, 0
	s_add_u32 s28, s26, 0x100
	v_mov_b32_e32 v0, 0
	s_addc_u32 s29, s27, 0
	s_mov_b32 s26, 0
	v_mov_b32_e32 v1, v0
	v_mov_b32_e32 v2, v0
	v_mov_b32_e32 v3, v0
	v_mov_b32_e32 v4, v0
	v_mov_b32_e32 v5, v0
	v_mov_b32_e32 v6, v0
	v_mov_b32_e32 v7, v0
	v_mov_b32_e32 v16, v0
	v_mov_b32_e32 v17, v0
	v_mov_b32_e32 v18, v0
	v_mov_b32_e32 v19, v0
	v_mov_b32_e32 v20, v0
	v_mov_b32_e32 v21, v0
	v_mov_b32_e32 v22, v0
	v_mov_b32_e32 v23, v0
	v_mov_b32_e32 v32, v0
	v_mov_b32_e32 v33, v0
	v_mov_b32_e32 v34, v0
	v_mov_b32_e32 v35, v0
	v_mov_b32_e32 v36, v0
	v_mov_b32_e32 v37, v0
	v_mov_b32_e32 v38, v0
	v_mov_b32_e32 v39, v0
	v_mov_b32_e32 v48, v0
	v_mov_b32_e32 v49, v0
	v_mov_b32_e32 v50, v0
	v_mov_b32_e32 v51, v0
	v_mov_b32_e32 v52, v0
	v_mov_b32_e32 v53, v0
	v_mov_b32_e32 v54, v0
	v_mov_b32_e32 v55, v0
	v_mov_b32_e32 v8, v0
	v_mov_b32_e32 v9, v0
	v_mov_b32_e32 v10, v0
	v_mov_b32_e32 v11, v0
	v_mov_b32_e32 v12, v0
	v_mov_b32_e32 v13, v0
	v_mov_b32_e32 v14, v0
	v_mov_b32_e32 v15, v0
	v_mov_b32_e32 v24, v0
	v_mov_b32_e32 v25, v0
	v_mov_b32_e32 v26, v0
	v_mov_b32_e32 v27, v0
	v_mov_b32_e32 v28, v0
	v_mov_b32_e32 v29, v0
	v_mov_b32_e32 v30, v0
	v_mov_b32_e32 v31, v0
	v_mov_b32_e32 v40, v0
	v_mov_b32_e32 v41, v0
	v_mov_b32_e32 v42, v0
	v_mov_b32_e32 v43, v0
	v_mov_b32_e32 v44, v0
	v_mov_b32_e32 v45, v0
	v_mov_b32_e32 v46, v0
	v_mov_b32_e32 v47, v0
	v_mov_b32_e32 v56, v0
	v_mov_b32_e32 v57, v0
	v_mov_b32_e32 v58, v0
	v_mov_b32_e32 v59, v0
	v_mov_b32_e32 v60, v0
	v_mov_b32_e32 v61, v0
	v_mov_b32_e32 v62, v0
	v_mov_b32_e32 v63, v0
	v_mov_b32_e32 v64, v0
	v_mov_b32_e32 v65, v0
	v_mov_b32_e32 v66, v0
	v_mov_b32_e32 v67, v0
	v_mov_b32_e32 v68, v0
	v_mov_b32_e32 v69, v0
	v_mov_b32_e32 v70, v0
	v_mov_b32_e32 v71, v0
	v_mov_b32_e32 v80, v0
	v_mov_b32_e32 v81, v0
	v_mov_b32_e32 v82, v0
	v_mov_b32_e32 v83, v0
	v_mov_b32_e32 v84, v0
	v_mov_b32_e32 v85, v0
	v_mov_b32_e32 v86, v0
	v_mov_b32_e32 v87, v0
	v_mov_b32_e32 v96, v0
	v_mov_b32_e32 v97, v0
	v_mov_b32_e32 v98, v0
	v_mov_b32_e32 v99, v0
	v_mov_b32_e32 v100, v0
	v_mov_b32_e32 v101, v0
	v_mov_b32_e32 v102, v0
	v_mov_b32_e32 v103, v0
	v_mov_b32_e32 v112, v0
	v_mov_b32_e32 v113, v0
	v_mov_b32_e32 v114, v0
	v_mov_b32_e32 v115, v0
	v_mov_b32_e32 v116, v0
	v_mov_b32_e32 v117, v0
	v_mov_b32_e32 v118, v0
	v_mov_b32_e32 v119, v0
	v_mov_b32_e32 v72, v0
	v_mov_b32_e32 v73, v0
	v_mov_b32_e32 v74, v0
	v_mov_b32_e32 v75, v0
	v_mov_b32_e32 v76, v0
	v_mov_b32_e32 v77, v0
	v_mov_b32_e32 v78, v0
	v_mov_b32_e32 v79, v0
	v_mov_b32_e32 v88, v0
	v_mov_b32_e32 v89, v0
	v_mov_b32_e32 v90, v0
	v_mov_b32_e32 v91, v0
	v_mov_b32_e32 v92, v0
	v_mov_b32_e32 v93, v0
	v_mov_b32_e32 v94, v0
	v_mov_b32_e32 v95, v0
	v_mov_b32_e32 v104, v0
	v_mov_b32_e32 v105, v0
	v_mov_b32_e32 v106, v0
	v_mov_b32_e32 v107, v0
	v_mov_b32_e32 v108, v0
	v_mov_b32_e32 v109, v0
	v_mov_b32_e32 v110, v0
	v_mov_b32_e32 v111, v0
	v_mov_b32_e32 v120, v0
	v_mov_b32_e32 v121, v0
	v_mov_b32_e32 v122, v0
	v_mov_b32_e32 v123, v0
	v_mov_b32_e32 v124, v0
	v_mov_b32_e32 v125, v0
	v_mov_b32_e32 v126, v0
	v_mov_b32_e32 v127, v0
	s_mov_b64 s[58:59], 0x80
	.p2align	6

; #define LAS __attribute__((address_space(3)))
;     ...
;         const bool has_next = S.next(ui + 1, nxt);
;         const unsigned rsoff = (unsigned)STAGE_BYTES + (unsigned)(ui & 1) * 1024u;
;         if constexpr (Epi::NEEDS_RS) { if (wid < 4) __builtin_amdgcn_global_load_lds((const unsigned*)(E.rsv + cur.pm * 256 + wid * 64 + lane), (LAS unsigned*)(lds + rsoff + wid * 256), 4, 0, 0); }
;         const char* nA = has_next ? (const char*)g.A + (size_t)nxt.pm * tstepA + (size_t)nxt.pn * APN : cA; const char* nB = has_next ? (const char*)g.Bt + (size_t)nxt.pn * tstepB : cB;
;         for (int t = 0; t < nt; t += 2) {
;             const bool last = (t == nt - 2);
;             const char* a1 = cA + (size_t)(t + 1) * kstep;
;             const char* a2 = last ? nA : cA + (size_t)(t + 2) * kstep; const char* b2 = last ? nB : cB + (size_t)(t + 2) * kstep;
;             const char* a3 = a2 + kstep; const char* b3 = b2 + kstep;
;     ...
; #pragma unroll
;         for (int a = 0; a < 2; ++a)
; #pragma unroll
;             for (int b = 0; b < 2; ++b)
; #pragma unroll
;                 for (int m = 0; m < 4; ++m)
; #pragma unroll
;                     for (int n = 0; n < 2; ++n) acc[a][b][m][n] = (f32x4){0.f, 0.f, 0.f, 0.f};
;         cur = nxt; cA = nA; cB = nB; ++ui;
.LBB0_551:
	s_ashr_i32 s21, s20, 31
	s_lshl_b64 s[24:25], s[20:21], 19
	v_readlane_b32 s52, v254, 28
	v_readlane_b32 s53, v254, 29
	s_add_u32 s24, s52, s24
	v_mov_b32_e32 v127, 0
	s_addc_u32 s25, s53, s25
	s_andn2_b64 vcc, exec, s[8:9]
	v_mov_b32_e32 v126, v127
	v_mov_b32_e32 v125, v127
	v_mov_b32_e32 v124, v127
	v_mov_b32_e32 v123, v127
	v_mov_b32_e32 v122, v127
	v_mov_b32_e32 v121, v127
	v_mov_b32_e32 v120, v127
	v_mov_b32_e32 v111, v127
	v_mov_b32_e32 v110, v127
	v_mov_b32_e32 v109, v127
	v_mov_b32_e32 v108, v127
	v_mov_b32_e32 v107, v127
	v_mov_b32_e32 v106, v127
	v_mov_b32_e32 v105, v127
	v_mov_b32_e32 v104, v127
	v_mov_b32_e32 v95, v127
	v_mov_b32_e32 v94, v127
	v_mov_b32_e32 v93, v127
	v_mov_b32_e32 v92, v127
	v_mov_b32_e32 v91, v127
	v_mov_b32_e32 v90, v127
	v_mov_b32_e32 v89, v127
	v_mov_b32_e32 v88, v127
	v_mov_b32_e32 v79, v127
	v_mov_b32_e32 v78, v127
	v_mov_b32_e32 v77, v127
	v_mov_b32_e32 v76, v127
	v_mov_b32_e32 v75, v127
	v_mov_b32_e32 v74, v127
	v_mov_b32_e32 v73, v127
	v_mov_b32_e32 v72, v127
	v_mov_b32_e32 v119, v127
	v_mov_b32_e32 v118, v127
	v_mov_b32_e32 v117, v127
	v_mov_b32_e32 v116, v127
	v_mov_b32_e32 v115, v127
	v_mov_b32_e32 v114, v127
	v_mov_b32_e32 v113, v127
	s_waitcnt lgkmcnt(0)
	v_mov_b32_e32 v112, v127
	v_mov_b32_e32 v103, v127
	v_mov_b32_e32 v102, v127
	v_mov_b32_e32 v101, v127
	v_mov_b32_e32 v100, v127
	v_mov_b32_e32 v99, v127
	v_mov_b32_e32 v98, v127
	v_mov_b32_e32 v97, v127
	v_mov_b32_e32 v96, v127
	v_mov_b32_e32 v87, v127
	v_mov_b32_e32 v86, v127
	v_mov_b32_e32 v85, v127
	v_mov_b32_e32 v84, v127
	v_mov_b32_e32 v83, v127
	v_mov_b32_e32 v82, v127
	v_mov_b32_e32 v81, v127
	v_mov_b32_e32 v80, v127
	v_mov_b32_e32 v71, v127
	v_mov_b32_e32 v70, v127
	v_mov_b32_e32 v69, v127
	v_mov_b32_e32 v68, v127
	v_mov_b32_e32 v67, v127
	v_mov_b32_e32 v66, v127
	v_mov_b32_e32 v65, v127
	v_mov_b32_e32 v64, v127
	v_mov_b32_e32 v63, v127
	v_mov_b32_e32 v62, v127
	v_mov_b32_e32 v61, v127
	v_mov_b32_e32 v60, v127
	v_mov_b32_e32 v59, v127
	v_mov_b32_e32 v58, v127
	v_mov_b32_e32 v57, v127
	v_mov_b32_e32 v56, v127
	v_mov_b32_e32 v47, v127
	v_mov_b32_e32 v46, v127
	v_mov_b32_e32 v45, v127
	v_mov_b32_e32 v44, v127
	v_mov_b32_e32 v43, v127
	v_mov_b32_e32 v42, v127
	v_mov_b32_e32 v41, v127
	v_mov_b32_e32 v40, v127
	v_mov_b32_e32 v31, v127
	v_mov_b32_e32 v30, v127
	v_mov_b32_e32 v29, v127
	v_mov_b32_e32 v28, v127
	v_mov_b32_e32 v27, v127
	v_mov_b32_e32 v26, v127
	v_mov_b32_e32 v25, v127
	v_mov_b32_e32 v24, v127
	v_mov_b32_e32 v15, v127
	v_mov_b32_e32 v14, v127
	v_mov_b32_e32 v13, v127
	v_mov_b32_e32 v12, v127
	v_mov_b32_e32 v11, v127
	v_mov_b32_e32 v10, v127
	v_mov_b32_e32 v9, v127
	v_mov_b32_e32 v8, v127
	v_mov_b32_e32 v55, v127
	v_mov_b32_e32 v54, v127
	v_mov_b32_e32 v53, v127
	v_mov_b32_e32 v52, v127
	v_mov_b32_e32 v51, v127
	v_mov_b32_e32 v50, v127
	v_mov_b32_e32 v49, v127
	v_mov_b32_e32 v48, v127
	v_mov_b32_e32 v39, v127
	v_mov_b32_e32 v38, v127
	v_mov_b32_e32 v37, v127
	v_mov_b32_e32 v36, v127
	v_mov_b32_e32 v35, v127
	v_mov_b32_e32 v34, v127
	v_mov_b32_e32 v33, v127
	v_mov_b32_e32 v32, v127
	v_mov_b32_e32 v23, v127
	v_mov_b32_e32 v22, v127
	v_mov_b32_e32 v21, v127
	v_mov_b32_e32 v20, v127
	v_mov_b32_e32 v19, v127
	v_mov_b32_e32 v18, v127
	v_mov_b32_e32 v17, v127
	v_mov_b32_e32 v16, v127
	v_mov_b32_e32 v7, v127
	v_mov_b32_e32 v6, v127
	v_mov_b32_e32 v5, v127
	v_mov_b32_e32 v4, v127
	v_mov_b32_e32 v3, v127
	v_mov_b32_e32 v2, v127
	v_mov_b32_e32 v1, v127
	v_mov_b32_e32 v0, v127
	s_cbranch_vccnz .LBB0_554
	s_and_b64 s[12:13], s[12:13], exec
	s_cselect_b32 s21, s25, s29
	s_cselect_b32 s51, s24, s28
	s_add_u32 s12, s28, 0x40080
	s_addc_u32 s13, s29, 0
	s_add_u32 s28, s26, 0x100
	v_mov_b32_e32 v0, 0
	s_addc_u32 s29, s27, 0
	s_mov_b32 s26, 0
	v_mov_b32_e32 v1, v0
	v_mov_b32_e32 v2, v0
	v_mov_b32_e32 v3, v0
	v_mov_b32_e32 v4, v0
	v_mov_b32_e32 v5, v0
	v_mov_b32_e32 v6, v0
	v_mov_b32_e32 v7, v0
	v_mov_b32_e32 v16, v0
	v_mov_b32_e32 v17, v0
	v_mov_b32_e32 v18, v0
	v_mov_b32_e32 v19, v0
	v_mov_b32_e32 v20, v0
	v_mov_b32_e32 v21, v0
	v_mov_b32_e32 v22, v0
	v_mov_b32_e32 v23, v0
	v_mov_b32_e32 v32, v0
	v_mov_b32_e32 v33, v0
	v_mov_b32_e32 v34, v0
	v_mov_b32_e32 v35, v0
	v_mov_b32_e32 v36, v0
	v_mov_b32_e32 v37, v0
	v_mov_b32_e32 v38, v0
	v_mov_b32_e32 v39, v0
	v_mov_b32_e32 v48, v0
	v_mov_b32_e32 v49, v0
	v_mov_b32_e32 v50, v0
	v_mov_b32_e32 v51, v0
	v_mov_b32_e32 v52, v0
	v_mov_b32_e32 v53, v0
	v_mov_b32_e32 v54, v0
	v_mov_b32_e32 v55, v0
	v_mov_b32_e32 v8, v0
	v_mov_b32_e32 v9, v0
	v_mov_b32_e32 v10, v0
	v_mov_b32_e32 v11, v0
	v_mov_b32_e32 v12, v0
	v_mov_b32_e32 v13, v0
	v_mov_b32_e32 v14, v0
	v_mov_b32_e32 v15, v0
	v_mov_b32_e32 v24, v0
	v_mov_b32_e32 v25, v0
	v_mov_b32_e32 v26, v0
	v_mov_b32_e32 v27, v0
	v_mov_b32_e32 v28, v0
	v_mov_b32_e32 v29, v0
	v_mov_b32_e32 v30, v0
	v_mov_b32_e32 v31, v0
	v_mov_b32_e32 v40, v0
	v_mov_b32_e32 v41, v0
	v_mov_b32_e32 v42, v0
	v_mov_b32_e32 v43, v0
	v_mov_b32_e32 v44, v0
	v_mov_b32_e32 v45, v0
	v_mov_b32_e32 v46, v0
	v_mov_b32_e32 v47, v0
	v_mov_b32_e32 v56, v0
	v_mov_b32_e32 v57, v0
	v_mov_b32_e32 v58, v0
	v_mov_b32_e32 v59, v0
	v_mov_b32_e32 v60, v0
	v_mov_b32_e32 v61, v0
	v_mov_b32_e32 v62, v0
	v_mov_b32_e32 v63, v0
	v_mov_b32_e32 v64, v0
	v_mov_b32_e32 v65, v0
	v_mov_b32_e32 v66, v0
	v_mov_b32_e32 v67, v0
	v_mov_b32_e32 v68, v0
	v_mov_b32_e32 v69, v0
	v_mov_b32_e32 v70, v0
	v_mov_b32_e32 v71, v0
	v_mov_b32_e32 v80, v0
	v_mov_b32_e32 v81, v0
	v_mov_b32_e32 v82, v0
	v_mov_b32_e32 v83, v0
	v_mov_b32_e32 v84, v0
	v_mov_b32_e32 v85, v0
	v_mov_b32_e32 v86, v0
	v_mov_b32_e32 v87, v0
	v_mov_b32_e32 v96, v0
	v_mov_b32_e32 v97, v0
	v_mov_b32_e32 v98, v0
	v_mov_b32_e32 v99, v0
	v_mov_b32_e32 v100, v0
	v_mov_b32_e32 v101, v0
	v_mov_b32_e32 v102, v0
	v_mov_b32_e32 v103, v0
	v_mov_b32_e32 v112, v0
	v_mov_b32_e32 v113, v0
	v_mov_b32_e32 v114, v0
	v_mov_b32_e32 v115, v0
	v_mov_b32_e32 v116, v0
	v_mov_b32_e32 v117, v0
	v_mov_b32_e32 v118, v0
	v_mov_b32_e32 v119, v0
	v_mov_b32_e32 v72, v0
	v_mov_b32_e32 v73, v0
	v_mov_b32_e32 v74, v0
	v_mov_b32_e32 v75, v0
	v_mov_b32_e32 v76, v0
	v_mov_b32_e32 v77, v0
	v_mov_b32_e32 v78, v0
	v_mov_b32_e32 v79, v0
	v_mov_b32_e32 v88, v0
	v_mov_b32_e32 v89, v0
	v_mov_b32_e32 v90, v0
	v_mov_b32_e32 v91, v0
	v_mov_b32_e32 v92, v0
	v_mov_b32_e32 v93, v0
	v_mov_b32_e32 v94, v0
	v_mov_b32_e32 v95, v0
	v_mov_b32_e32 v104, v0
	v_mov_b32_e32 v105, v0
	v_mov_b32_e32 v106, v0
	v_mov_b32_e32 v107, v0
	v_mov_b32_e32 v108, v0
	v_mov_b32_e32 v109, v0
	v_mov_b32_e32 v110, v0
	v_mov_b32_e32 v111, v0
	v_mov_b32_e32 v120, v0
	v_mov_b32_e32 v121, v0
	v_mov_b32_e32 v122, v0
	v_mov_b32_e32 v123, v0
	v_mov_b32_e32 v124, v0
	v_mov_b32_e32 v125, v0
	v_mov_b32_e32 v126, v0
	v_mov_b32_e32 v127, v0
	s_mov_b64 s[58:59], 0x80
	.p2align	6
